# stacked: permlane-swap residual reductions plus static younger-half priority on top of the loader-VALU-free K-loops and double-buffered rstd reads
# speedup vs baseline: 1.0153x; 1.0040x over previous
.LBB0_493:
	s_setprio 0
	s_lshl_b32 s17, s17, 8
	v_lshl_or_b32 v208, s16, 8, v236
	v_add_u32_e32 v120, s17, v233
	v_ashrrev_i32_e32 v209, 31, v208
	v_lshlrev_b64 v[224:225], 1, v[208:209]
	v_ashrrev_i32_e32 v121, 31, v120
	v_lshl_add_u64 v[122:123], s[20:21], 0, v[224:225]
	v_lshlrev_b64 v[226:227], 11, v[120:121]
	v_lshl_add_u64 v[124:125], v[122:123], 0, v[226:227]
	global_load_dwordx4 v[250:253], v[124:125], off
	global_load_dwordx4 v[184:187], v[124:125], off offset:256
	v_or_b32_e32 v124, 16, v120
	v_ashrrev_i32_e32 v125, 31, v124
	v_lshlrev_b64 v[222:223], 11, v[124:125]
	v_lshl_add_u64 v[124:125], v[122:123], 0, v[222:223]
	global_load_dwordx4 v[180:183], v[124:125], off
	global_load_dwordx4 v[176:179], v[124:125], off offset:256
	v_or_b32_e32 v124, 32, v120
	v_or_b32_e32 v120, 48, v120
	v_ashrrev_i32_e32 v125, 31, v124
	v_ashrrev_i32_e32 v121, 31, v120
	v_lshlrev_b64 v[220:221], 11, v[124:125]
	v_lshlrev_b64 v[218:219], 11, v[120:121]
	s_mov_b64 s[2:3], 0x40000
	v_lshl_add_u64 v[124:125], v[122:123], 0, v[220:221]
	v_lshl_add_u64 v[120:121], v[122:123], 0, v[218:219]
	v_lshl_add_u64 v[216:217], v[226:227], 0, s[2:3]
	s_mov_b64 s[30:31], 0x48000
	global_load_dwordx4 v[172:175], v[124:125], off
	global_load_dwordx4 v[160:163], v[124:125], off offset:256
	global_load_dwordx4 v[156:159], v[120:121], off
	global_load_dwordx4 v[152:155], v[120:121], off offset:256
	v_lshl_add_u64 v[120:121], v[122:123], 0, v[216:217]
	v_lshl_add_u64 v[214:215], v[226:227], 0, s[30:31]
	s_mov_b64 s[30:31], 0x50000
	global_load_dwordx4 v[148:151], v[120:121], off
	global_load_dwordx4 v[140:143], v[120:121], off offset:256
	v_lshl_add_u64 v[120:121], v[122:123], 0, v[214:215]
	v_lshl_add_u64 v[212:213], v[226:227], 0, s[30:31]
	s_mov_b64 s[30:31], 0x58000
	global_load_dwordx4 v[144:147], v[120:121], off
	global_load_dwordx4 v[136:139], v[120:121], off offset:256
	v_lshl_add_u64 v[120:121], v[122:123], 0, v[212:213]
	v_lshl_add_u64 v[210:211], v[226:227], 0, s[30:31]
	global_load_dwordx4 v[132:135], v[120:121], off
	global_load_dwordx4 v[128:131], v[120:121], off offset:256
	v_lshl_add_u64 v[120:121], v[122:123], 0, v[210:211]
	global_load_dwordx4 v[124:127], v[120:121], off
	s_nop 0
	global_load_dwordx4 v[120:123], v[120:121], off offset:256
	s_waitcnt vmcnt(0) lgkmcnt(0)
	v_lshlrev_b32_e32 v254, 16, v250
	v_fmac_f32_e32 v254, v235, v168
	v_and_b32_e32 v168, 0xffff0000, v250
	v_fmac_f32_e32 v168, v235, v169
	v_lshlrev_b32_e32 v169, 16, v251
	v_fmac_f32_e32 v169, v235, v170
	v_and_b32_e32 v170, 0xffff0000, v251
	v_fmac_f32_e32 v170, v235, v171
	v_cvt_pk_bf16_f32 v168, v254, v168
	v_cvt_pk_bf16_f32 v169, v169, v170
	v_lshlrev_b32_e32 v170, 16, v252
	v_fmac_f32_e32 v170, v235, v164
	v_and_b32_e32 v164, 0xffff0000, v252
	v_fmac_f32_e32 v164, v235, v165
	v_cvt_pk_bf16_f32 v170, v170, v164
	v_lshlrev_b32_e32 v164, 16, v253
	v_and_b32_e32 v165, 0xffff0000, v253
	v_fmac_f32_e32 v164, v235, v166
	v_fmac_f32_e32 v165, v235, v167
	v_cvt_pk_bf16_f32 v171, v164, v165
	v_lshl_add_u64 v[164:165], s[20:21], 0, v[226:227]
	v_lshl_add_u64 v[164:165], v[164:165], 0, v[224:225]
	v_and_b32_e32 v167, 0xffff0000, v168
	global_store_dwordx4 v[164:165], v[168:171], off
	v_lshlrev_b32_e32 v166, 16, v168
	v_mul_f32_e32 v167, v167, v167
	v_and_b32_e32 v168, 0xffff0000, v169
	v_fmac_f32_e32 v167, v166, v166
	v_lshlrev_b32_e32 v166, 16, v169
	v_mul_f32_e32 v168, v168, v168
	v_fmac_f32_e32 v168, v166, v166
	v_add_f32_e32 v166, v167, v168
	v_and_b32_e32 v168, 0xffff0000, v170
	v_lshlrev_b32_e32 v167, 16, v170
	v_mul_f32_e32 v168, v168, v168
	v_fmac_f32_e32 v168, v167, v167
	v_add_f32_e32 v166, v166, v168
	v_and_b32_e32 v168, 0xffff0000, v171
	v_lshlrev_b32_e32 v167, 16, v171
	v_mul_f32_e32 v168, v168, v168
	v_fmac_f32_e32 v168, v167, v167
	v_lshlrev_b32_e32 v167, 16, v184
	v_fmac_f32_e32 v167, v235, v116
	v_and_b32_e32 v116, 0xffff0000, v184
	v_fmac_f32_e32 v116, v235, v117
	v_lshlrev_b32_e32 v117, 16, v185
	v_fmac_f32_e32 v117, v235, v118
	v_and_b32_e32 v118, 0xffff0000, v185
	v_fmac_f32_e32 v118, v235, v119
	v_cvt_pk_bf16_f32 v116, v167, v116
	v_cvt_pk_bf16_f32 v117, v117, v118
	v_lshlrev_b32_e32 v118, 16, v186
	v_fmac_f32_e32 v118, v235, v112
	v_and_b32_e32 v112, 0xffff0000, v186
	v_fmac_f32_e32 v112, v235, v113
	v_and_b32_e32 v113, 0xffff0000, v187
	v_cvt_pk_bf16_f32 v118, v118, v112
	v_lshlrev_b32_e32 v112, 16, v187
	v_fmac_f32_e32 v113, v235, v115
	v_fmac_f32_e32 v112, v235, v114
	v_cvt_pk_bf16_f32 v119, v112, v113
	v_and_b32_e32 v113, 0xffff0000, v116
	v_lshlrev_b32_e32 v112, 16, v116
	v_mul_f32_e32 v113, v113, v113
	v_and_b32_e32 v114, 0xffff0000, v117
	v_fmac_f32_e32 v113, v112, v112
	v_lshlrev_b32_e32 v112, 16, v117
	v_mul_f32_e32 v114, v114, v114
	v_fmac_f32_e32 v114, v112, v112
	v_add_f32_e32 v112, v113, v114
	v_and_b32_e32 v114, 0xffff0000, v118
	v_lshlrev_b32_e32 v113, 16, v118
	v_mul_f32_e32 v114, v114, v114
	v_fmac_f32_e32 v114, v113, v113
	v_add_f32_e32 v112, v112, v114
	v_and_b32_e32 v114, 0xffff0000, v119
	v_lshlrev_b32_e32 v113, 16, v119
	v_mul_f32_e32 v114, v114, v114
	v_fmac_f32_e32 v114, v113, v113
	v_add_f32_e32 v166, v166, v168
	v_add_f32_e32 v112, v112, v114
	v_add_f32_e32 v112, v166, v112
	v_mov_b32_e32 v113, v112
	global_store_dwordx4 v[164:165], v[116:119], off offset:256
	s_nop 1
	v_permlane16_swap_b32_e32 v112, v113
	v_add_f32_e32 v112, v112, v113
	v_mov_b32_e32 v113, v112
	s_nop 1
	v_permlane32_swap_b32_e32 v112, v113
	s_and_saveexec_b64 s[30:31], s[4:5]
	s_cbranch_execz .LBB0_495
	v_add_f32_e32 v112, v112, v113
	ds_write_b32 v240, v112
